# DSA: prefetch next half-tile's selection-mask bits (static in LDS) one tile ahead
# speedup vs baseline: 1.0010x; 1.0010x over previous
; template <int MODE> ...
;     const int tid = opaque_tid(), lane = tid & 63, r32 = lane & 31, hi = lane >> 5; const int wid = __builtin_amdgcn_readfirstlane(tid >> 6);
;     LAS float* cbuf = (LAS float*)(lds + 36864); LAS float* wt = (LAS float*)(lds + 45056); LAS unsigned* flags = (LAS unsigned*)(lds + (MODE == 1 ? 92160 + 64 : 45088));
;     const size_t rowbase = (size_t)b * SEQ; const int qw = qb * 256 + wid * 32, q = qw + r32; const int ntiles = 4 * (qb + 1), td = qw >> 6;
;     const int skr = tid >> 3, sch = tid & 7;
;     const GAS bf16_t* kg = HA + (rowbase + skr) * LDH + kcol + sch * 8;
;     const GAS bf16_t* vg = HA + (rowbase + skr) * LDH + vcol + sch * 8;
;     const int t_first = (MODE == 1) ? ntiles - 1 : 0;
;     u32x4 kreg = *(const GAS u32x4*)(kg + (size_t)t_first * 64 * LDH), vreg = *(const GAS u32x4*)(vg + (size_t)t_first * 64 * LDH);
;     float cq = 0.f;
;     if (MODE == 0) {
;         float lf[4];
; #pragma unroll
;         for (int i = 0; i < 4; ++i) { const float x = FL[(rowbase + 4 * tid + i) * 8] + bfv; lf[i] = (fminf(x, 0.f) - __logf(1.f + __expf(-fabsf(x)))) * L2E; }
;         const float s1 = lf[0], s2 = s1 + lf[1], s3 = s2 + lf[2], s4 = s3 + lf[3];
;         float v = s4;
; #pragma unroll
;         for (int off = 1; off < 64; off <<= 1) { const float n = __shfl_up(v, off); if (lane >= off) v += n; }
;         if (lane == 63) wt[wid] = v;
;         __syncthreads();
;         float base = 0.f;
; #pragma unroll
;         for (int w = 0; w < 8; ++w) { const float x = wt[w]; if (w < wid) base += x; }
;         const float ex = base + v - s4;
;         *(LAS f32x4*)(cbuf + 4 * tid) = (f32x4){ex + s1, ex + s2, ex + s3, ex + s4};
;         __syncthreads();
;         cq = cbuf[q];
;     }
;     if (MODE == 1) { if (tid < 8) flags[tid] = 0u; }
;     bf16x8 qr[4];
;     { const GAS bf16_t* qp = HA + (rowbase + q) * LDH + qcol + hi * 8;
; #pragma unroll
;       for (int d0 = 0; d0 < 4; ++d0) qr[d0] = *(const GAS bf16x8*)(qp + d0 * 16); }
;     bf16x8 T0, T1, ONES;
;     if (MODE == 1) {
; #pragma unroll
;         for (int j = 0; j < 8; ++j) { const int kk = 8 * (j >> 2) + 4 * hi + (j & 3); T0[j] = (kk > r32) ? (short)0x3F80 : (short)0; T1[j] = (16 + kk > r32) ? (short)0x3F80 : (short)0; ONES[j] = (short)0x3F80; }
;     }
;     LAS unsigned long long* mlds = (LAS unsigned long long*)(lds + 45568) + (wid * 32 + r32) * 33;
.LBB0_918:
	s_or_b64 exec, exec, s[8:9]
	v_readlane_b32 s8, v252, 28
	s_waitcnt lgkmcnt(0)
	s_barrier
	v_mov_b32_e32 v1, s8
	ds_read_b32 v1, v1
	s_mov_b64 s[8:9], -1
	s_waitcnt lgkmcnt(0)
	v_readfirstlane_b32 s10, v1
	s_cmpk_gt_i32 s10, 0x4ff
	s_cbranch_scc1 .LBB0_915
	s_mul_hi_i32 s8, s10, 0x99999999
	s_lshr_b32 s9, s8, 31
	s_ashr_i32 s8, s8, 6
	s_add_i32 s8, s8, s9
	s_add_i32 s12, s8, 7
	s_mul_hi_i32 s8, s10, 0x66666667
	s_lshr_b32 s9, s8, 31
	s_ashr_i32 s8, s8, 6
	s_add_i32 s8, s8, s9
	s_mulk_i32 s8, 0xa0
	v_mov_b32_e32 v1, v230
	s_sub_i32 s9, s10, s8
	s_mul_i32 s8, s9, 0x6667
	v_readfirstlane_b32 s13, v1
	s_ashr_i32 s13, s13, 1
	s_lshr_b32 s10, s8, 31
	s_ashr_i32 s8, s8, 17
	s_lshl_b32 s14, s12, 8
	s_and_b32 s15, s13, 0xffffffe0
	s_add_i32 s8, s8, s10
	s_waitcnt vmcnt(0)
	v_and_b32_e32 v54, 31, v1
	s_add_i32 s15, s15, s14
	s_bfe_i64 s[10:11], s[8:9], 0x100000
	v_or_b32_e32 v2, s15, v54
	s_lshl_b64 s[10:11], s[10:11], 11
	v_ashrrev_i32_e32 v3, 31, v2
	v_lshl_add_u64 v[98:99], s[10:11], 0, v[2:3]
	v_bfe_u32 v55, v1, 5, 1
	v_lshlrev_b64 v[2:3], 8, v[98:99]
	v_lshl_add_u64 v[2:3], s[4:5], 0, v[2:3]
	v_lshlrev_b32_e32 v42, 7, v55
	v_mov_b32_e32 v43, v0
	v_lshl_add_u64 v[30:31], v[2:3], 0, v[42:43]
	global_load_dwordx4 v[2:5], v[30:31], off offset:16
	global_load_dwordx4 v[6:9], v[30:31], off
	v_ashrrev_i32_e32 v56, 3, v1
	global_load_dwordx4 v[10:13], v[30:31], off offset:48
	global_load_dwordx4 v[14:17], v[30:31], off offset:32
	v_add_u32_e32 v18, s10, v56
	v_mov_b64_e32 v[44:45], s[2:3]
	s_movk_i32 s14, 0x1880
	s_mul_i32 s8, s8, 5
	v_mad_i64_i32 v[34:35], s[10:11], v18, s14, v[44:45]
	global_load_dwordx4 v[18:21], v[30:31], off offset:80
	global_load_dwordx4 v[22:25], v[30:31], off offset:64
	s_sub_i32 s8, s9, s8
	v_lshlrev_b32_e32 v26, 4, v1
	s_sext_i32_i16 s8, s8
	v_and_b32_e32 v46, 0x70, v26
	v_mov_b32_e32 v47, v0
	global_load_dwordx4 v[26:29], v[30:31], off offset:112
	s_nop 0
	global_load_dwordx4 v[30:33], v[30:31], off offset:96
	s_lshl_b32 s8, s8, 6
	v_mad_u64_u32 v[44:45], s[10:11], v98, s14, v[44:45]
	v_lshl_add_u64 v[48:49], v[34:35], 0, v[46:47]
	s_movk_i32 s16, 0x1000
	v_mad_i32_i24 v45, v99, s14, v45
	s_ashr_i32 s9, s8, 31
	v_add_co_u32_e32 v38, vcc, s16, v48
	v_lshl_add_u64 v[44:45], s[8:9], 1, v[44:45]
	v_lshlrev_b32_e32 v50, 4, v55
	v_mov_b32_e32 v51, v0
	v_addc_co_u32_e32 v39, vcc, 0, v49, vcc
	v_lshl_add_u64 v[44:45], v[44:45], 0, v[50:51]
	s_mov_b64 s[10:11], 0x1080
	v_lshl_add_u64 v[52:53], v[44:45], 0, s[10:11]
	v_add_co_u32_e32 v44, vcc, s16, v44
	global_load_dwordx4 v[34:37], v[38:39], off offset:768
	s_nop 0
	global_load_dwordx4 v[38:41], v[38:39], off offset:896
	v_addc_co_u32_e32 v45, vcc, 0, v45, vcc
	global_load_dwordx4 v[66:69], v[52:53], off offset:32
	global_load_dwordx4 v[70:73], v[52:53], off offset:64
	global_load_dwordx4 v[74:77], v[44:45], off offset:128
	global_load_dwordx4 v[78:81], v[52:53], off offset:96
	v_add_co_u32_e32 v44, vcc, s51, v48
	s_mov_b64 s[10:11], 0x1300
	s_nop 0
	v_addc_co_u32_e32 v45, vcc, 0, v49, vcc
	global_load_dwordx4 v[82:85], v[44:45], off offset:768
	global_load_dwordx4 v[86:89], v[44:45], off offset:896
	v_lshl_add_u64 v[102:103], v[48:49], 0, s[10:11]
	s_mov_b64 s[10:11], 0x1380
	v_lshl_add_u64 v[104:105], v[48:49], 0, s[10:11]
	v_mov_b32_e32 v44, s13
	s_movk_i32 s10, 0xffe0
	v_bfi_b32 v44, s10, v44, v1
	s_movk_i32 s10, 0x108
	v_mul_lo_u32 v44, v44, s10
	v_add3_u32 v42, 0, v44, v42
	v_add_u32_e32 v45, 0xb200, v42
	s_movk_i32 s10, 0x90
	v_lshlrev_b32_e32 v100, 2, v55
	v_lshlrev_b32_e32 v43, 3, v1
	s_lshl_b32 s12, s12, 2
	s_add_i32 s16, s12, 4
	s_mov_b32 s23, 0
	s_ashr_i32 s17, s15, 6
	s_or_b32 s18, s12, 3
	v_or_b32_e32 v106, 32, v100
	v_mov_b32_e32 v112, 0
	v_mov_b32_e32 v111, 0
	s_waitcnt vmcnt(14)
	ds_write2_b64 v45, v[6:7], v[8:9] offset1:1
	v_add_u32_e32 v6, 0xb210, v42
	ds_write2_b64 v6, v[2:3], v[4:5] offset1:1
	v_add_u32_e32 v2, 0xb220, v42
	s_waitcnt vmcnt(12)
	ds_write2_b64 v2, v[14:15], v[16:17] offset1:1
	v_add_u32_e32 v2, 0xb230, v42
	ds_write2_b64 v2, v[10:11], v[12:13] offset1:1
	v_add_u32_e32 v2, 0xb240, v42
	v_and_b32_e32 v3, 24, v43
	s_waitcnt vmcnt(10)
	ds_write2_b64 v2, v[22:23], v[24:25] offset1:1
	v_add_u32_e32 v2, 0xb250, v42
	ds_write2_b64 v2, v[18:19], v[20:21] offset1:1
	v_add_u32_e32 v2, 0xb260, v42
	v_mov_b32_e32 v14, v0
	v_mov_b32_e32 v15, v0
	s_waitcnt vmcnt(8)
	ds_write2_b64 v2, v[30:31], v[32:33] offset1:1
	v_add_u32_e32 v2, 0xb270, v42
	ds_write2_b64 v2, v[26:27], v[28:29] offset1:1
	v_mul_lo_u32 v2, v56, s10
	v_add3_u32 v101, 0, v2, v46
	v_lshrrev_b32_e32 v2, 2, v1
	v_and_or_b32 v2, v2, 3, v100
	v_and_b32_e32 v1, 16, v1
	v_mad_u32_u24 v2, v2, s10, 0
	v_lshlrev_b32_e32 v1, 1, v1
	v_add_u32_e32 v16, 0, v50
	v_mul_u32_u24_e32 v17, 0x90, v54
	v_add3_u32 v107, v2, v1, v3
	v_mov_b32_e32 v1, v0
	v_mov_b32_e32 v2, v0
	v_mov_b32_e32 v3, v0
	v_mov_b32_e32 v4, v0
	v_mov_b32_e32 v5, v0
	v_mov_b32_e32 v6, v0
	v_mov_b32_e32 v7, v0
	v_mov_b32_e32 v8, v0
	v_mov_b32_e32 v9, v0
	v_mov_b32_e32 v10, v0
	v_mov_b32_e32 v11, v0
	v_mov_b32_e32 v12, v0
	v_mov_b32_e32 v13, v0
	v_mov_b64_e32 v[32:33], v[14:15]
	s_add_i32 s10, 0, 0xb200
	v_add_u32_e32 v113, v16, v17
	v_mov_b64_e32 v[30:31], v[12:13]
	v_mov_b64_e32 v[28:29], v[10:11]
	v_mov_b64_e32 v[26:27], v[8:9]
	v_mov_b64_e32 v[24:25], v[6:7]
	v_mov_b64_e32 v[22:23], v[4:5]
	v_mov_b64_e32 v[20:21], v[2:3]
	v_mov_b64_e32 v[18:19], v[0:1]
	v_mov_b64_e32 v[16:17], v[14:15]
	v_add_u32_e32 v109, s10, v44
	s_mov_b64 s[10:11], -1
	v_mov_b64_e32 v[14:15], v[12:13]
	v_mov_b64_e32 v[12:13], v[10:11]
	v_mov_b64_e32 v[10:11], v[8:9]
	v_mov_b64_e32 v[8:9], v[6:7]
	v_mov_b64_e32 v[6:7], v[4:5]
	v_mov_b64_e32 v[4:5], v[2:3]
	v_mov_b64_e32 v[2:3], v[0:1]
	s_waitcnt vmcnt(7)
	ds_write_b128 v101, v[34:37]
	s_waitcnt vmcnt(6)
	ds_write_b128 v101, v[38:41] offset:9216
	s_waitcnt lgkmcnt(0)
	s_barrier
	ds_read_b64 v[134:135], v109
.LBB0_920:
	s_add_i32 s19, s23, 2
	s_min_i32 s14, s19, s18
	s_mul_i32 s12, s14, 0x62000
	s_mov_b32 s13, 0
	v_lshl_add_u64 v[34:35], s[12:13], 0, v[102:103]
	s_mul_i32 s12, s14, 0x62000
	s_mov_b32 s13, 0
	v_lshl_add_u64 v[36:37], s[12:13], 0, v[104:105]
	global_load_dwordx4 v[90:93], v[34:35], off
	global_load_dwordx4 v[94:97], v[36:37], off
	s_cmp_gt_i32 s23, s17
	s_cbranch_scc1 .LBB0_926
	ds_read_b128 v[118:121], v113
	ds_read_b128 v[122:125], v113 offset:32
	ds_read_b128 v[126:129], v113 offset:64
	ds_read_b128 v[130:133], v113 offset:96
	ds_read_b128 v[182:185], v113 offset:4608
	ds_read_b128 v[186:189], v113 offset:4640
	ds_read_b128 v[190:193], v113 offset:4672
	ds_read_b128 v[242:245], v113 offset:4704
	v_sub_f32_e32 v1, 0, v112
	s_xor_b64 s[10:11], s[10:11], -1
	s_waitcnt lgkmcnt(8)
	v_lshrrev_b64 v[114:115], v100, v[134:135]
	v_lshrrev_b64 v[116:117], v106, v[134:135]
	v_bfe_i32 v34, v114, 0, 1
	v_bfe_i32 v35, v114, 1, 1
	v_bfe_i32 v36, v114, 2, 1
	v_bfe_i32 v37, v114, 3, 1
	v_bfe_i32 v38, v114, 8, 1
	v_bfe_i32 v39, v114, 9, 1
	v_bfe_i32 v40, v114, 10, 1
	v_bfe_i32 v41, v114, 11, 1
	v_bfe_i32 v42, v114, 16, 1
	v_bfe_i32 v43, v114, 17, 1
	v_bfe_i32 v44, v114, 18, 1
	v_bfe_i32 v45, v114, 19, 1
	v_bfe_i32 v46, v114, 24, 1
	v_bfe_i32 v47, v114, 25, 1
	v_bfe_i32 v48, v114, 26, 1
	v_bfe_i32 v49, v114, 27, 1
	v_bfi_b32 v34, v34, v1, v232
	v_bfi_b32 v35, v35, v1, v232
	v_bfi_b32 v36, v36, v1, v232
	v_bfi_b32 v37, v37, v1, v232
	v_bfi_b32 v38, v38, v1, v232
	v_bfi_b32 v39, v39, v1, v232
	v_bfi_b32 v40, v40, v1, v232
	v_bfi_b32 v41, v41, v1, v232
	v_bfi_b32 v42, v42, v1, v232
	v_bfi_b32 v43, v43, v1, v232
	v_bfi_b32 v44, v44, v1, v232
	v_bfi_b32 v45, v45, v1, v232
	v_bfi_b32 v46, v46, v1, v232
	v_bfi_b32 v47, v47, v1, v232
	v_bfi_b32 v48, v48, v1, v232
	v_bfi_b32 v49, v49, v1, v232
	s_waitcnt vmcnt(4) lgkmcnt(4)
	s_nop 0
	v_mfma_f32_32x32x16_bf16 v[34:49], v[118:121], v[74:77], v[34:49]
	v_bfe_i32 v50, v116, 0, 1
	v_bfe_i32 v51, v116, 1, 1
	v_bfe_i32 v52, v116, 2, 1
	v_bfe_i32 v53, v116, 3, 1
	v_bfe_i32 v54, v116, 8, 1
	v_bfe_i32 v55, v116, 9, 1
	v_bfe_i32 v56, v116, 10, 1
	v_bfe_i32 v57, v116, 11, 1
	s_waitcnt lgkmcnt(4)
	v_mfma_f32_32x32x16_bf16 v[34:49], v[122:125], v[66:69], v[34:49]
	v_bfe_i32 v58, v116, 16, 1
	v_bfe_i32 v59, v116, 17, 1
	v_bfe_i32 v60, v116, 18, 1
	v_bfe_i32 v61, v116, 19, 1
	v_bfe_i32 v62, v116, 24, 1
	v_bfe_i32 v63, v116, 25, 1
	v_bfe_i32 v64, v116, 26, 1
	v_bfe_i32 v65, v116, 27, 1
	s_waitcnt lgkmcnt(4)
	v_mfma_f32_32x32x16_bf16 v[34:49], v[126:129], v[70:73], v[34:49]
	v_bfi_b32 v50, v50, v1, v232
	v_bfi_b32 v51, v51, v1, v232
	v_bfi_b32 v52, v52, v1, v232
	v_bfi_b32 v53, v53, v1, v232
	v_bfi_b32 v54, v54, v1, v232
	v_bfi_b32 v55, v55, v1, v232
	v_bfi_b32 v56, v56, v1, v232
	v_bfi_b32 v57, v57, v1, v232
	s_waitcnt lgkmcnt(0)
	v_mfma_f32_32x32x16_bf16 v[34:49], v[130:133], v[78:81], v[34:49]
	v_bfi_b32 v58, v58, v1, v232
	v_bfi_b32 v59, v59, v1, v232
	v_bfi_b32 v60, v60, v1, v232
	v_bfi_b32 v61, v61, v1, v232
	v_bfi_b32 v62, v62, v1, v232
	v_bfi_b32 v63, v63, v1, v232
	v_bfi_b32 v64, v64, v1, v232
	v_bfi_b32 v65, v65, v1, v232
	s_nop 1
	v_mfma_f32_32x32x16_bf16 v[50:65], v[182:185], v[74:77], v[50:65]
	ds_read_b64_tr_b16 v[198:199], v107 offset:9216
	ds_read_b64_tr_b16 v[200:201], v107 offset:10368
	ds_read_b64_tr_b16 v[202:203], v107 offset:11520
	ds_read_b64_tr_b16 v[204:205], v107 offset:12672
	v_mfma_f32_32x32x16_bf16 v[50:65], v[186:189], v[66:69], v[50:65]
	ds_read_b64_tr_b16 v[206:207], v107 offset:13824
	ds_read_b64_tr_b16 v[208:209], v107 offset:14976
	ds_read_b64_tr_b16 v[210:211], v107 offset:16128
	ds_read_b64_tr_b16 v[212:213], v107 offset:17280
	v_mfma_f32_32x32x16_bf16 v[50:65], v[190:193], v[70:73], v[50:65]
	ds_read_b64_tr_b16 v[214:215], v107 offset:9280
	ds_read_b64_tr_b16 v[216:217], v107 offset:10432
	ds_read_b64_tr_b16 v[218:219], v107 offset:11584
	ds_read_b64_tr_b16 v[220:221], v107 offset:12736
	v_mfma_f32_32x32x16_bf16 v[50:65], v[242:245], v[78:81], v[50:65]
	ds_read_b64_tr_b16 v[234:235], v107 offset:13888
	ds_read_b64_tr_b16 v[236:237], v107 offset:15040
	ds_read_b64_tr_b16 v[238:239], v107 offset:16192
	ds_read_b64_tr_b16 v[240:241], v107 offset:17344
	s_nop 1
	ds_read_b64 v[176:177], v109 offset:8
	v_max3_f32 v108, v34, v35, v36
	v_max3_f32 v110, v37, v38, v39
	v_max3_f32 v114, v40, v41, v42
	v_max3_f32 v1, v43, v44, v45
	v_max3_f32 v108, v108, v46, v47
	v_max3_f32 v110, v110, v48, v49
	v_max3_f32 v114, v114, v50, v51
	v_max3_f32 v1, v1, v52, v53
	v_max3_f32 v108, v108, v54, v55
	v_max3_f32 v110, v110, v56, v57
	v_max3_f32 v114, v114, v58, v59
	v_max3_f32 v1, v1, v60, v61
	v_max3_f32 v108, v108, v62, v63
	v_max3_f32 v110, v110, v64, v65
	v_max3_f32 v1, v1, v114, s82
	v_max3_f32 v1, v1, v108, v110
	v_mov_b32_e32 v108, v1
	s_nop 1
	v_permlane32_swap_b32_e32 v108, v1
	v_max_f32_e32 v1, v1, v108
	s_and_saveexec_b64 s[12:13], s[10:11]
	s_xor_b64 s[10:11], exec, s[12:13]
	s_cbranch_execnz .LBB0_934
	s_or_saveexec_b64 s[12:13], s[10:11]
	s_mov_b64 s[10:11], 0
	s_xor_b64 exec, exec, s[12:13]
	s_cbranch_execnz .LBB0_937

; #define LAS __attribute__((address_space(3)))
; #define STAGE_TILE(bufi, KR, VR) do { LAS bf16_t* Ks_ = (LAS bf16_t*)(lds + (bufi) * 18432); LAS bf16_t* Vs_ = (LAS bf16_t*)(lds + (bufi) * 18432 + 9216); \
;         *(LAS u32x4*)(Ks_ + skr * 72 + sch * 8) = KR; *(LAS u32x4*)(Vs_ + skr * 72 + sch * 8) = VR; } while (0)
; #define LOAD_TILE(KR, VR, tl) do { KR = *(const GAS u32x4*)(kg + (size_t)(tl) * 64 * LDH); VR = *(const GAS u32x4*)(vg + (size_t)(tl) * 64 * LDH); } while (0)
; template <int MODE> ...
;     ...
;         STAGE_TILE(1, kB, vB);
;         __syncthreads();
;         if (MODE == 1) { const u32x4 fa = *(const LAS u32x4*)flags, fb = *(const LAS u32x4*)(flags + 4); if ((fa.x & fa.y & fa.z & fa.w & fb.x & fb.y & fb.z & fb.w) != 0u) break; }
;         LOAD_TILE(kB, vB, TILE_OF(min(it + 3, ntiles - 1)));
.LBB0_926:
	s_add_i32 s12, s23, 3
	s_min_i32 s14, s12, s18
	s_mul_i32 s12, s14, 0x62000
	s_mov_b32 s13, 0
	v_lshl_add_u64 v[34:35], s[12:13], 0, v[102:103]
	s_waitcnt vmcnt(3)
	ds_write_b128 v101, v[82:85] offset:18432
	s_waitcnt vmcnt(2)
	ds_write_b128 v101, v[86:89] offset:27648
	s_waitcnt lgkmcnt(0)
	s_barrier
	s_mul_i32 s12, s14, 0x62000
	s_mov_b32 s13, 0
	v_lshl_add_u64 v[36:37], s[12:13], 0, v[104:105]
	global_load_dwordx4 v[82:85], v[34:35], off
	global_load_dwordx4 v[86:89], v[36:37], off
	s_cmp_ge_i32 s23, s17
	s_cbranch_scc1 .LBB0_932
	ds_read_b128 v[118:121], v113 offset:18432
	ds_read_b128 v[122:125], v113 offset:18464
	ds_read_b128 v[126:129], v113 offset:18496
	ds_read_b128 v[130:133], v113 offset:18528
	ds_read_b128 v[182:185], v113 offset:23040
	ds_read_b128 v[186:189], v113 offset:23072
	ds_read_b128 v[190:193], v113 offset:23104
	ds_read_b128 v[242:245], v113 offset:23136
	v_sub_f32_e32 v1, 0, v112
	s_xor_b64 s[10:11], s[10:11], -1
	s_waitcnt lgkmcnt(8)
	v_lshrrev_b64 v[114:115], v100, v[176:177]
	v_lshrrev_b64 v[116:117], v106, v[176:177]
	v_bfe_i32 v34, v114, 0, 1
	v_bfe_i32 v35, v114, 1, 1
	v_bfe_i32 v36, v114, 2, 1
	v_bfe_i32 v37, v114, 3, 1
	v_bfe_i32 v38, v114, 8, 1
	v_bfe_i32 v39, v114, 9, 1
	v_bfe_i32 v40, v114, 10, 1
	v_bfe_i32 v41, v114, 11, 1
	v_bfe_i32 v42, v114, 16, 1
	v_bfe_i32 v43, v114, 17, 1
	v_bfe_i32 v44, v114, 18, 1
	v_bfe_i32 v45, v114, 19, 1
	v_bfe_i32 v46, v114, 24, 1
	v_bfe_i32 v47, v114, 25, 1
	v_bfe_i32 v48, v114, 26, 1
	v_bfe_i32 v49, v114, 27, 1
	v_bfi_b32 v34, v34, v1, v232
	v_bfi_b32 v35, v35, v1, v232
	v_bfi_b32 v36, v36, v1, v232
	v_bfi_b32 v37, v37, v1, v232
	v_bfi_b32 v38, v38, v1, v232
	v_bfi_b32 v39, v39, v1, v232
	v_bfi_b32 v40, v40, v1, v232
	v_bfi_b32 v41, v41, v1, v232
	v_bfi_b32 v42, v42, v1, v232
	v_bfi_b32 v43, v43, v1, v232
	v_bfi_b32 v44, v44, v1, v232
	v_bfi_b32 v45, v45, v1, v232
	v_bfi_b32 v46, v46, v1, v232
	v_bfi_b32 v47, v47, v1, v232
	v_bfi_b32 v48, v48, v1, v232
	v_bfi_b32 v49, v49, v1, v232
	s_waitcnt lgkmcnt(4)
	s_nop 0
	v_mfma_f32_32x32x16_bf16 v[34:49], v[118:121], v[74:77], v[34:49]
	v_bfe_i32 v50, v116, 0, 1
	v_bfe_i32 v51, v116, 1, 1
	v_bfe_i32 v52, v116, 2, 1
	v_bfe_i32 v53, v116, 3, 1
	v_bfe_i32 v54, v116, 8, 1
	v_bfe_i32 v55, v116, 9, 1
	v_bfe_i32 v56, v116, 10, 1
	v_bfe_i32 v57, v116, 11, 1
	s_waitcnt lgkmcnt(4)
	v_mfma_f32_32x32x16_bf16 v[34:49], v[122:125], v[66:69], v[34:49]
	v_bfe_i32 v58, v116, 16, 1
	v_bfe_i32 v59, v116, 17, 1
	v_bfe_i32 v60, v116, 18, 1
	v_bfe_i32 v61, v116, 19, 1
	v_bfe_i32 v62, v116, 24, 1
	v_bfe_i32 v63, v116, 25, 1
	v_bfe_i32 v64, v116, 26, 1
	v_bfe_i32 v65, v116, 27, 1
	s_waitcnt lgkmcnt(4)
	v_mfma_f32_32x32x16_bf16 v[34:49], v[126:129], v[70:73], v[34:49]
	v_bfi_b32 v50, v50, v1, v232
	v_bfi_b32 v51, v51, v1, v232
	v_bfi_b32 v52, v52, v1, v232
	v_bfi_b32 v53, v53, v1, v232
	v_bfi_b32 v54, v54, v1, v232
	v_bfi_b32 v55, v55, v1, v232
	v_bfi_b32 v56, v56, v1, v232
	v_bfi_b32 v57, v57, v1, v232
	s_waitcnt lgkmcnt(0)
	v_mfma_f32_32x32x16_bf16 v[34:49], v[130:133], v[78:81], v[34:49]
	v_bfi_b32 v58, v58, v1, v232
	v_bfi_b32 v59, v59, v1, v232
	v_bfi_b32 v60, v60, v1, v232
	v_bfi_b32 v61, v61, v1, v232
	v_bfi_b32 v62, v62, v1, v232
	v_bfi_b32 v63, v63, v1, v232
	v_bfi_b32 v64, v64, v1, v232
	v_bfi_b32 v65, v65, v1, v232
	s_nop 1
	v_mfma_f32_32x32x16_bf16 v[50:65], v[182:185], v[74:77], v[50:65]
	ds_read_b64_tr_b16 v[198:199], v107 offset:27648
	ds_read_b64_tr_b16 v[200:201], v107 offset:28800
	ds_read_b64_tr_b16 v[202:203], v107 offset:29952
	ds_read_b64_tr_b16 v[204:205], v107 offset:31104
	v_mfma_f32_32x32x16_bf16 v[50:65], v[186:189], v[66:69], v[50:65]
	ds_read_b64_tr_b16 v[206:207], v107 offset:32256
	ds_read_b64_tr_b16 v[208:209], v107 offset:33408
	ds_read_b64_tr_b16 v[210:211], v107 offset:34560
	ds_read_b64_tr_b16 v[212:213], v107 offset:35712
	v_mfma_f32_32x32x16_bf16 v[50:65], v[190:193], v[70:73], v[50:65]
	ds_read_b64_tr_b16 v[214:215], v107 offset:27712
	ds_read_b64_tr_b16 v[216:217], v107 offset:28864
	ds_read_b64_tr_b16 v[218:219], v107 offset:30016
	ds_read_b64_tr_b16 v[220:221], v107 offset:31168
	v_mfma_f32_32x32x16_bf16 v[50:65], v[242:245], v[78:81], v[50:65]
	ds_read_b64_tr_b16 v[234:235], v107 offset:32320
	ds_read_b64_tr_b16 v[236:237], v107 offset:33472
	ds_read_b64_tr_b16 v[238:239], v107 offset:34624
	ds_read_b64_tr_b16 v[240:241], v107 offset:35776
	s_nop 1
	ds_read_b64 v[134:135], v109 offset:16
	v_max3_f32 v108, v34, v35, v36
	v_max3_f32 v110, v37, v38, v39
	v_max3_f32 v114, v40, v41, v42
	v_max3_f32 v1, v43, v44, v45
	v_max3_f32 v108, v108, v46, v47
	v_max3_f32 v110, v110, v48, v49
	v_max3_f32 v114, v114, v50, v51
	v_max3_f32 v1, v1, v52, v53
	v_max3_f32 v108, v108, v54, v55
	v_max3_f32 v110, v110, v56, v57
	v_max3_f32 v114, v114, v58, v59
	v_max3_f32 v1, v1, v60, v61
	v_max3_f32 v108, v108, v62, v63
	v_max3_f32 v110, v110, v64, v65
	v_max3_f32 v1, v1, v114, s82
	v_max3_f32 v1, v1, v108, v110
	v_mov_b32_e32 v108, v1
	s_nop 1
	v_permlane32_swap_b32_e32 v108, v1
	v_max_f32_e32 v1, v1, v108
	s_and_saveexec_b64 s[12:13], s[10:11]
	s_xor_b64 s[10:11], exec, s[12:13]
	s_cbranch_execnz .LBB0_940
	s_or_saveexec_b64 s[12:13], s[10:11]
	s_mov_b64 s[10:11], 0
	s_xor_b64 exec, exec, s[12:13]
	s_cbranch_execnz .LBB0_943
